# pool mixer phase rewritten by hand: window sums on the matrix cores (transposed LDS reads x exact 0/1 band weights), result feeds the group map directly (no pooled LDS image), two barriers per item, r
# speedup vs baseline: 1.0411x; 1.0083x over previous
.LBB0_320:
	v_readlane_b32 s2, v244, 31
	s_waitcnt vmcnt(0)
	s_cmpk_lt_i32 s2, 0x300
	s_cselect_b64 s[8:9], -1, 0
	v_readlane_b32 s72, v244, 32
	v_readlane_b32 s50, v244, 36
	v_readlane_b32 s70, v244, 2
	v_readlane_b32 s76, v244, 38
	v_mov_b32_e32 v55, v214
	s_and_b64 vcc, exec, s[8:9]
	v_readlane_b32 s49, v244, 28
	v_readlane_b32 s73, v244, 33
	v_readlane_b32 s74, v244, 34
	v_readlane_b32 s75, v244, 35
	v_readlane_b32 s51, v244, 37
	v_readlane_b32 s64, v244, 30
	v_readlane_b32 s65, v244, 29
	v_readlane_b32 s71, v244, 3
	v_readlane_b32 s77, v244, 39
	s_waitcnt vmcnt(0) lgkmcnt(0)
	s_barrier
	s_cbranch_vccz .LBB0_336
	v_and_b32_e32 v176, 63, v214
	v_and_b32_e32 v200, 15, v176
	v_lshrrev_b32_e32 v201, 4, v176
	v_readfirstlane_b32 s15, v214
	s_lshr_b32 s15, s15, 6
	s_and_b32 s0, s15, 3
	s_lshr_b32 s1, s15, 2
	s_add_u32 s10, s74, 0x8000000
	s_addc_u32 s11, s75, 0
	s_add_u32 s12, s74, 0x18800000
	s_addc_u32 s13, s75, 0
	v_mov_b32_e32 v204, 0x3f80
	v_mov_b32_e32 v205, 0x3f800000
	v_lshrrev_b32_e32 v176, 2, v200
	v_lshl_add_u32 v176, v201, 2, v176
	v_mul_u32_u24_e32 v176, 0x210, v176
	v_and_b32_e32 v177, 3, v200
	v_lshl_add_u32 v202, v177, 3, v176
	v_mul_u32_u24_e32 v176, 0x210, v200
	v_lshl_add_u32 v203, v201, 3, v176
	v_and_b32_e32 v176, 31, v214
	v_lshlrev_b32_e32 v206, 4, v176
	v_lshrrev_b32_e32 v207, 5, v214
	v_mul_u32_u24_e32 v177, 0x210, v207
	v_add_u32_e32 v128, v177, v206
	s_lshl_b32 s15, 1, s0
	v_mov_b32_e32 v208, s15
	v_lshlrev_b32_e32 v210, 4, v200
	s_lshl_b32 s15, s0, 2
	v_add_u32_e32 v209, s15, v210
	v_add_u32_e32 v209, 0x12900, v209
	v_add_u32_e32 v210, 0x12900, v210
	s_lshl_b32 s15, s0, 7
	v_lshl_add_u32 v211, v201, 3, s15
	v_cmp_eq_u32_e64 s[6:7], 0, v201
	s_mov_b32 s4, s2
	s_lshl_b32 s14, s4, 6
	s_cmpk_lt_i32 s4, 0x100
	s_mov_b32 s3, 0x7fffc000
	s_cselect_b32 s3, 0xfffff800, s3
	s_movk_i32 s19, 0x4000
	s_cselect_b32 s19, 0x800, s19
	s_and_b32 s3, s3, s14
	s_sub_i32 s14, s14, s3
	v_mov_b32_e32 v132, 0
	v_mov_b32_e32 v133, 0
	v_mov_b32_e32 v134, 0
	v_mov_b32_e32 v135, 0
	v_mov_b32_e32 v136, 0
	v_mov_b32_e32 v137, 0
	v_mov_b32_e32 v138, 0
	v_mov_b32_e32 v139, 0
	v_mov_b32_e32 v140, 0
	v_mov_b32_e32 v141, 0
	v_mov_b32_e32 v142, 0
	v_mov_b32_e32 v143, 0
	v_mov_b32_e32 v144, 0
	v_mov_b32_e32 v145, 0
	v_mov_b32_e32 v146, 0
	v_mov_b32_e32 v147, 0
	v_mov_b32_e32 v148, 0
	v_mov_b32_e32 v149, 0
	v_mov_b32_e32 v150, 0
	v_mov_b32_e32 v151, 0
	v_add_u32_e32 v129, s14, v207
	v_add_u32_e32 v129, -8, v129
	v_mov_b32_e32 v131, v129
	v_cmp_gt_u32_e32 vcc, s19, v131
	v_add_u32_e32 v152, s3, v131
	v_lshl_add_u32 v152, v152, 9, v206
	s_and_saveexec_b64 s[30:31], vcc
	global_load_dwordx4 v[132:135], v152, s[10:11]
	s_mov_b64 exec, s[30:31]
	v_add_u32_e32 v131, 16, v129
	v_cmp_gt_u32_e32 vcc, s19, v131
	v_add_u32_e32 v152, s3, v131
	v_lshl_add_u32 v152, v152, 9, v206
	s_and_saveexec_b64 s[30:31], vcc
	global_load_dwordx4 v[136:139], v152, s[10:11]
	s_mov_b64 exec, s[30:31]
	v_add_u32_e32 v131, 32, v129
	v_cmp_gt_u32_e32 vcc, s19, v131
	v_add_u32_e32 v152, s3, v131
	v_lshl_add_u32 v152, v152, 9, v206
	s_and_saveexec_b64 s[30:31], vcc
	global_load_dwordx4 v[140:143], v152, s[10:11]
	s_mov_b64 exec, s[30:31]
	v_add_u32_e32 v131, 48, v129
	v_cmp_gt_u32_e32 vcc, s19, v131
	v_add_u32_e32 v152, s3, v131
	v_lshl_add_u32 v152, v152, 9, v206
	s_and_saveexec_b64 s[30:31], vcc
	global_load_dwordx4 v[144:147], v152, s[10:11]
	s_mov_b64 exec, s[30:31]
	v_add_u32_e32 v131, 64, v129
	v_cmp_gt_u32_e32 vcc, s19, v131
	v_add_u32_e32 v152, s3, v131
	v_lshl_add_u32 v152, v152, 9, v206
	s_and_saveexec_b64 s[30:31], vcc
	global_load_dwordx4 v[148:151], v152, s[10:11]
	s_mov_b64 exec, s[30:31]
	s_lshl_b32 s15, s0, 14
	s_add_u32 s24, s26, s15
	s_addc_u32 s25, s27, 0
	v_lshlrev_b32_e32 v176, 10, v201
	v_lshl_add_u32 v176, v200, 2, v176
	v_mov_b32_e32 v177, v176
	global_load_dword v84, v177, s[24:25] offset:0
	global_load_dword v85, v177, s[24:25] offset:256
	global_load_dword v86, v177, s[24:25] offset:512
	global_load_dword v87, v177, s[24:25] offset:768
	global_load_dword v88, v177, s[24:25] offset:64
	global_load_dword v89, v177, s[24:25] offset:320
	global_load_dword v90, v177, s[24:25] offset:576
	global_load_dword v91, v177, s[24:25] offset:832
	global_load_dword v92, v177, s[24:25] offset:128
	global_load_dword v93, v177, s[24:25] offset:384
	global_load_dword v94, v177, s[24:25] offset:640
	global_load_dword v95, v177, s[24:25] offset:896
	global_load_dword v96, v177, s[24:25] offset:192
	global_load_dword v97, v177, s[24:25] offset:448
	global_load_dword v98, v177, s[24:25] offset:704
	global_load_dword v99, v177, s[24:25] offset:960
	v_add_u32_e32 v178, 0x1000, v176
	global_load_dword v100, v178, s[24:25] offset:0
	global_load_dword v101, v178, s[24:25] offset:256
	global_load_dword v102, v178, s[24:25] offset:512
	global_load_dword v103, v178, s[24:25] offset:768
	global_load_dword v104, v178, s[24:25] offset:64
	global_load_dword v105, v178, s[24:25] offset:320
	global_load_dword v106, v178, s[24:25] offset:576
	global_load_dword v107, v178, s[24:25] offset:832
	global_load_dword v108, v178, s[24:25] offset:128
	global_load_dword v109, v178, s[24:25] offset:384
	global_load_dword v110, v178, s[24:25] offset:640
	global_load_dword v111, v178, s[24:25] offset:896
	global_load_dword v112, v178, s[24:25] offset:192
	global_load_dword v113, v178, s[24:25] offset:448
	global_load_dword v114, v178, s[24:25] offset:704
	global_load_dword v115, v178, s[24:25] offset:960
	v_add_u32_e32 v179, 0x2000, v176
	global_load_dword v220, v179, s[24:25] offset:0
	global_load_dword v221, v179, s[24:25] offset:256
	global_load_dword v222, v179, s[24:25] offset:512
	global_load_dword v223, v179, s[24:25] offset:768
	global_load_dword v224, v179, s[24:25] offset:64
	global_load_dword v225, v179, s[24:25] offset:320
	global_load_dword v226, v179, s[24:25] offset:576
	global_load_dword v227, v179, s[24:25] offset:832
	global_load_dword v228, v179, s[24:25] offset:128
	global_load_dword v229, v179, s[24:25] offset:384
	global_load_dword v230, v179, s[24:25] offset:640
	global_load_dword v231, v179, s[24:25] offset:896
	global_load_dword v232, v179, s[24:25] offset:192
	global_load_dword v233, v179, s[24:25] offset:448
	global_load_dword v234, v179, s[24:25] offset:704
	global_load_dword v235, v179, s[24:25] offset:960
	v_add_u32_e32 v180, 0x3000, v176
	global_load_dword v236, v180, s[24:25] offset:0
	global_load_dword v237, v180, s[24:25] offset:256
	global_load_dword v238, v180, s[24:25] offset:512
	global_load_dword v239, v180, s[24:25] offset:768
	global_load_dword v240, v180, s[24:25] offset:64
	global_load_dword v241, v180, s[24:25] offset:320
	global_load_dword v242, v180, s[24:25] offset:576
	global_load_dword v243, v180, s[24:25] offset:832
	global_load_dword v245, v180, s[24:25] offset:128
	global_load_dword v246, v180, s[24:25] offset:384
	global_load_dword v247, v180, s[24:25] offset:640
	global_load_dword v248, v180, s[24:25] offset:896
	global_load_dword v249, v180, s[24:25] offset:192
	global_load_dword v250, v180, s[24:25] offset:448
	global_load_dword v251, v180, s[24:25] offset:704
	global_load_dword v252, v180, s[24:25] offset:960
	s_lshl_b32 s15, s0, 8
	s_add_u32 s16, s28, s15
	s_addc_u32 s17, s29, 0
	v_lshlrev_b32_e32 v182, 4, v201
	global_load_dwordx4 v[32:35], v182, s[16:17] offset:0
	global_load_dwordx4 v[36:39], v182, s[16:17] offset:64
	global_load_dwordx4 v[40:43], v182, s[16:17] offset:128
	global_load_dwordx4 v[44:47], v182, s[16:17] offset:192
	s_waitcnt vmcnt(0)
	v_cvt_pk_bf16_f32 v0, v84, v85
	v_cvt_pk_bf16_f32 v1, v86, v87
	v_cvt_pk_bf16_f32 v8, v88, v89
	v_cvt_pk_bf16_f32 v9, v90, v91
	v_cvt_pk_bf16_f32 v16, v92, v93
	v_cvt_pk_bf16_f32 v17, v94, v95
	v_cvt_pk_bf16_f32 v24, v96, v97
	v_cvt_pk_bf16_f32 v25, v98, v99
	v_cvt_pk_bf16_f32 v2, v100, v101
	v_cvt_pk_bf16_f32 v3, v102, v103
	v_cvt_pk_bf16_f32 v10, v104, v105
	v_cvt_pk_bf16_f32 v11, v106, v107
	v_cvt_pk_bf16_f32 v18, v108, v109
	v_cvt_pk_bf16_f32 v19, v110, v111
	v_cvt_pk_bf16_f32 v26, v112, v113
	v_cvt_pk_bf16_f32 v27, v114, v115
	v_cvt_pk_bf16_f32 v4, v220, v221
	v_cvt_pk_bf16_f32 v5, v222, v223
	v_cvt_pk_bf16_f32 v12, v224, v225
	v_cvt_pk_bf16_f32 v13, v226, v227
	v_cvt_pk_bf16_f32 v20, v228, v229
	v_cvt_pk_bf16_f32 v21, v230, v231
	v_cvt_pk_bf16_f32 v28, v232, v233
	v_cvt_pk_bf16_f32 v29, v234, v235
	v_cvt_pk_bf16_f32 v6, v236, v237
	v_cvt_pk_bf16_f32 v7, v238, v239
	v_cvt_pk_bf16_f32 v14, v240, v241
	v_cvt_pk_bf16_f32 v15, v242, v243
	v_cvt_pk_bf16_f32 v22, v245, v246
	v_cvt_pk_bf16_f32 v23, v247, v248
	v_cvt_pk_bf16_f32 v30, v249, v250
	v_cvt_pk_bf16_f32 v31, v251, v252
.Lpx_item:
	s_waitcnt vmcnt(8)
	ds_write_b128 v128, v[132:135] offset:0
	ds_write_b128 v128, v[136:139] offset:8448
	ds_write_b128 v128, v[140:143] offset:16896
	ds_write_b128 v128, v[144:147] offset:25344
	ds_write_b128 v128, v[148:151] offset:33792
	s_add_i32 s101, s4, s66
	s_cmpk_gt_i32 s101, 0x2ff
	s_cbranch_scc1 .Lpx_noreq
	s_lshl_b32 s98, s101, 6
	s_cmpk_lt_i32 s101, 0x100
	s_mov_b32 s99, 0x7fffc000
	s_cselect_b32 s99, 0xfffff800, s99
	s_movk_i32 s100, 0x4000
	s_cselect_b32 s100, 0x800, s100
	s_and_b32 s99, s99, s98
	s_sub_i32 s98, s98, s99
	s_nop 0
	v_mov_b32_e32 v132, 0
	v_mov_b32_e32 v133, 0
	v_mov_b32_e32 v134, 0
	v_mov_b32_e32 v135, 0
	v_mov_b32_e32 v136, 0
	v_mov_b32_e32 v137, 0
	v_mov_b32_e32 v138, 0
	v_mov_b32_e32 v139, 0
	v_mov_b32_e32 v140, 0
	v_mov_b32_e32 v141, 0
	v_mov_b32_e32 v142, 0
	v_mov_b32_e32 v143, 0
	v_mov_b32_e32 v144, 0
	v_mov_b32_e32 v145, 0
	v_mov_b32_e32 v146, 0
	v_mov_b32_e32 v147, 0
	v_mov_b32_e32 v148, 0
	v_mov_b32_e32 v149, 0
	v_mov_b32_e32 v150, 0
	v_mov_b32_e32 v151, 0
	v_add_u32_e32 v129, s98, v207
	v_add_u32_e32 v129, -8, v129
	v_mov_b32_e32 v131, v129
	v_cmp_gt_u32_e32 vcc, s100, v131
	v_add_u32_e32 v152, s99, v131
	v_lshl_add_u32 v152, v152, 9, v206
	s_and_saveexec_b64 s[30:31], vcc
	global_load_dwordx4 v[132:135], v152, s[10:11]
	s_mov_b64 exec, s[30:31]
	v_add_u32_e32 v131, 16, v129
	v_cmp_gt_u32_e32 vcc, s100, v131
	v_add_u32_e32 v152, s99, v131
	v_lshl_add_u32 v152, v152, 9, v206
	s_and_saveexec_b64 s[30:31], vcc
	global_load_dwordx4 v[136:139], v152, s[10:11]
	s_mov_b64 exec, s[30:31]
	v_add_u32_e32 v131, 32, v129
	v_cmp_gt_u32_e32 vcc, s100, v131
	v_add_u32_e32 v152, s99, v131
	v_lshl_add_u32 v152, v152, 9, v206
	s_and_saveexec_b64 s[30:31], vcc
	global_load_dwordx4 v[140:143], v152, s[10:11]
	s_mov_b64 exec, s[30:31]
	v_add_u32_e32 v131, 48, v129
	v_cmp_gt_u32_e32 vcc, s100, v131
	v_add_u32_e32 v152, s99, v131
	v_lshl_add_u32 v152, v152, 9, v206
	s_and_saveexec_b64 s[30:31], vcc
	global_load_dwordx4 v[144:147], v152, s[10:11]
	s_mov_b64 exec, s[30:31]
	v_add_u32_e32 v131, 64, v129
	v_cmp_gt_u32_e32 vcc, s100, v131
	v_add_u32_e32 v152, s99, v131
	v_lshl_add_u32 v152, v152, 9, v206
	s_and_saveexec_b64 s[30:31], vcc
	global_load_dwordx4 v[148:151], v152, s[10:11]
	s_mov_b64 exec, s[30:31]
.Lpx_noreq:
	s_waitcnt lgkmcnt(0)
	s_barrier
	s_lshl_b32 s15, s1, 1
	s_mul_i32 s16, s15, 0x2100
	s_lshl_b32 s17, s0, 7
	s_add_i32 s16, s16, s17
	v_add_u32_e32 v176, s16, v202
	ds_read_b64_tr_b16 v[64:65], v176 offset:0
	ds_read_b64_tr_b16 v[66:67], v176 offset:32
	ds_read_b64_tr_b16 v[68:69], v176 offset:64
	ds_read_b64_tr_b16 v[70:71], v176 offset:96
	ds_read_b64_tr_b16 v[116:117], v176 offset:8448
	ds_read_b64_tr_b16 v[118:119], v176 offset:8480
	ds_read_b64_tr_b16 v[120:121], v176 offset:8512
	ds_read_b64_tr_b16 v[122:123], v176 offset:8544
	v_add_u32_e32 v177, s16, v203
	ds_read_b64 v[154:155], v177 offset:4224
	ds_read_b64 v[156:157], v177 offset:4256
	ds_read_b64 v[158:159], v177 offset:4288
	ds_read_b64 v[160:161], v177 offset:4320
	s_lshl_b32 s17, s15, 4
	s_add_i32 s18, s14, s17
	v_add_u32_e32 v178, s18, v200
	v_sub_u32_e32 v179, v178, v208
	v_max_i32_e32 v179, 0, v179
	v_add_u32_e32 v180, v178, v208
	v_min_i32_e32 v180, s19, v180
	v_sub_u32_e32 v213, v180, v179
	s_add_i32 s18, s18, -8
	v_subrev_u32_e32 v212, s18, v179
	v_lshlrev_b32_e32 v181, 2, v201
	v_sub_u32_e32 v212, v212, v181
	v_sub_u32_e32 v184, 0, v212
	v_sub_u32_e32 v185, 1, v212
	v_sub_u32_e32 v186, 2, v212
	v_sub_u32_e32 v187, 3, v212
	v_cmp_lt_u32_e64 s[20:21], v184, v213
	v_cmp_lt_u32_e64 s[24:25], v185, v213
	v_cmp_lt_u32_e64 s[26:27], v186, v213
	v_cmp_lt_u32_e64 s[28:29], v187, v213
	v_cndmask_b32_e64 v184, 0, v204, s[20:21]
	v_cndmask_b32_e64 v185, 0, v205, s[24:25]
	v_cndmask_b32_e64 v186, 0, v204, s[26:27]
	v_cndmask_b32_e64 v187, 0, v205, s[28:29]
	v_or_b32_e32 v72, v184, v185
	v_or_b32_e32 v73, v186, v187
	v_sub_u32_e32 v184, 16, v212
	v_sub_u32_e32 v185, 17, v212
	v_sub_u32_e32 v186, 18, v212
	v_sub_u32_e32 v187, 19, v212
	v_cmp_lt_u32_e64 s[20:21], v184, v213
	v_cmp_lt_u32_e64 s[24:25], v185, v213
	v_cmp_lt_u32_e64 s[26:27], v186, v213
	v_cmp_lt_u32_e64 s[28:29], v187, v213
	v_cndmask_b32_e64 v184, 0, v204, s[20:21]
	v_cndmask_b32_e64 v185, 0, v205, s[24:25]
	v_cndmask_b32_e64 v186, 0, v204, s[26:27]
	v_cndmask_b32_e64 v187, 0, v205, s[28:29]
	v_or_b32_e32 v74, v184, v185
	v_or_b32_e32 v75, v186, v187
	v_cvt_f32_i32_e32 v188, v213
	v_div_scale_f32 v189, s[20:21], v188, v188, 1.0
	v_rcp_f32_e32 v190, v189
	v_div_scale_f32 v191, vcc, 1.0, v188, 1.0
	v_fma_f32 v192, -v189, v190, 1.0
	v_fmac_f32_e32 v190, v192, v190
	v_mul_f32_e32 v192, v191, v190
	v_fma_f32 v193, -v189, v192, v191
	v_fmac_f32_e32 v192, v193, v190
	v_fma_f32 v189, -v189, v192, v191
	s_nop 1
	v_div_fmas_f32 v189, v189, v190, v192
	v_div_fixup_f32 v172, v189, v188, 1.0
	s_waitcnt lgkmcnt(0)
	v_mfma_f32_16x16x16_bf16 v[48:51], v[64:65], v[72:73], 0
	v_mfma_f32_16x16x16_bf16 v[52:55], v[66:67], v[72:73], 0
	v_mfma_f32_16x16x16_bf16 v[56:59], v[68:69], v[72:73], 0
	v_mfma_f32_16x16x16_bf16 v[60:63], v[70:71], v[72:73], 0
	v_mfma_f32_16x16x16_bf16 v[48:51], v[116:117], v[74:75], v[48:51]
	v_mfma_f32_16x16x16_bf16 v[52:55], v[118:119], v[74:75], v[52:55]
	v_mfma_f32_16x16x16_bf16 v[56:59], v[120:121], v[74:75], v[56:59]
	v_mfma_f32_16x16x16_bf16 v[60:63], v[122:123], v[74:75], v[60:63]
	v_and_b32_e32 v167, 0xffff0000, v154
	v_lshlrev_b32_e32 v166, 16, v154
	v_and_b32_e32 v169, 0xffff0000, v155
	v_lshlrev_b32_e32 v168, 16, v155
	s_nop 0
	v_pk_fma_f32 v[48:49], v[48:49], v[172:173], v[166:167] op_sel_hi:[1,0,1] neg_lo:[0,0,1] neg_hi:[0,0,1]
	v_pk_fma_f32 v[50:51], v[50:51], v[172:173], v[168:169] op_sel_hi:[1,0,1] neg_lo:[0,0,1] neg_hi:[0,0,1]
	s_nop 0
	v_cvt_pk_bf16_f32 v76, v48, v49
	v_cvt_pk_bf16_f32 v77, v50, v51
	v_and_b32_e32 v167, 0xffff0000, v156
	v_lshlrev_b32_e32 v166, 16, v156
	v_and_b32_e32 v169, 0xffff0000, v157
	v_lshlrev_b32_e32 v168, 16, v157
	v_pk_fma_f32 v[52:53], v[52:53], v[172:173], v[166:167] op_sel_hi:[1,0,1] neg_lo:[0,0,1] neg_hi:[0,0,1]
	v_pk_fma_f32 v[54:55], v[54:55], v[172:173], v[168:169] op_sel_hi:[1,0,1] neg_lo:[0,0,1] neg_hi:[0,0,1]
	s_nop 0
	v_cvt_pk_bf16_f32 v78, v52, v53
	v_cvt_pk_bf16_f32 v79, v54, v55
	v_and_b32_e32 v167, 0xffff0000, v158
	v_lshlrev_b32_e32 v166, 16, v158
	v_and_b32_e32 v169, 0xffff0000, v159
	v_lshlrev_b32_e32 v168, 16, v159
	v_pk_fma_f32 v[56:57], v[56:57], v[172:173], v[166:167] op_sel_hi:[1,0,1] neg_lo:[0,0,1] neg_hi:[0,0,1]
	v_pk_fma_f32 v[58:59], v[58:59], v[172:173], v[168:169] op_sel_hi:[1,0,1] neg_lo:[0,0,1] neg_hi:[0,0,1]
	s_nop 0
	v_cvt_pk_bf16_f32 v80, v56, v57
	v_cvt_pk_bf16_f32 v81, v58, v59
	v_and_b32_e32 v167, 0xffff0000, v160
	v_lshlrev_b32_e32 v166, 16, v160
	v_and_b32_e32 v169, 0xffff0000, v161
	v_lshlrev_b32_e32 v168, 16, v161
	v_pk_fma_f32 v[60:61], v[60:61], v[172:173], v[166:167] op_sel_hi:[1,0,1] neg_lo:[0,0,1] neg_hi:[0,0,1]
	v_pk_fma_f32 v[62:63], v[62:63], v[172:173], v[168:169] op_sel_hi:[1,0,1] neg_lo:[0,0,1] neg_hi:[0,0,1]
	s_nop 0
	v_cvt_pk_bf16_f32 v82, v60, v61
	v_cvt_pk_bf16_f32 v83, v62, v63
	v_mfma_f32_16x16x16_bf16 v[84:87], v[0:1], v[76:77], 0
	v_mfma_f32_16x16x16_bf16 v[88:91], v[8:9], v[76:77], 0
	v_mfma_f32_16x16x16_bf16 v[92:95], v[16:17], v[76:77], 0
	v_mfma_f32_16x16x16_bf16 v[96:99], v[24:25], v[76:77], 0
	v_mfma_f32_16x16x16_bf16 v[84:87], v[2:3], v[78:79], v[84:87]
	v_mfma_f32_16x16x16_bf16 v[88:91], v[10:11], v[78:79], v[88:91]
	v_mfma_f32_16x16x16_bf16 v[92:95], v[18:19], v[78:79], v[92:95]
	v_mfma_f32_16x16x16_bf16 v[96:99], v[26:27], v[78:79], v[96:99]
	v_mfma_f32_16x16x16_bf16 v[84:87], v[4:5], v[80:81], v[84:87]
	v_mfma_f32_16x16x16_bf16 v[88:91], v[12:13], v[80:81], v[88:91]
	v_mfma_f32_16x16x16_bf16 v[92:95], v[20:21], v[80:81], v[92:95]
	v_mfma_f32_16x16x16_bf16 v[96:99], v[28:29], v[80:81], v[96:99]
	v_mfma_f32_16x16x16_bf16 v[84:87], v[6:7], v[82:83], v[84:87]
	v_mfma_f32_16x16x16_bf16 v[88:91], v[14:15], v[82:83], v[88:91]
	v_mfma_f32_16x16x16_bf16 v[92:95], v[22:23], v[82:83], v[92:95]
	v_mfma_f32_16x16x16_bf16 v[96:99], v[30:31], v[82:83], v[96:99]
	s_nop 4
	v_pk_mul_f32 v[84:85], v[84:85], v[32:33]
	v_pk_mul_f32 v[86:87], v[86:87], v[34:35]
	v_pk_mul_f32 v[88:89], v[88:89], v[36:37]
	v_pk_mul_f32 v[90:91], v[90:91], v[38:39]
	v_pk_mul_f32 v[92:93], v[92:93], v[40:41]
	v_pk_mul_f32 v[94:95], v[94:95], v[42:43]
	v_pk_mul_f32 v[96:97], v[96:97], v[44:45]
	v_pk_mul_f32 v[98:99], v[98:99], v[46:47]
	v_mul_f32_e32 v163, v85, v85
	v_mul_f32_e32 v164, v87, v87
	v_fmac_f32_e32 v163, v84, v84
	v_fmac_f32_e32 v164, v86, v86
	v_add_f32_e32 v162, v163, v164
	v_mul_f32_e32 v163, v89, v89
	v_mul_f32_e32 v164, v91, v91
	v_fmac_f32_e32 v163, v88, v88
	v_fmac_f32_e32 v164, v90, v90
	v_add_f32_e32 v163, v163, v164
	v_add_f32_e32 v162, v162, v163
	v_mul_f32_e32 v163, v93, v93
	v_mul_f32_e32 v164, v95, v95
	v_fmac_f32_e32 v163, v92, v92
	v_fmac_f32_e32 v164, v94, v94
	v_add_f32_e32 v163, v163, v164
	v_add_f32_e32 v162, v162, v163
	v_mul_f32_e32 v163, v97, v97
	v_mul_f32_e32 v164, v99, v99
	v_fmac_f32_e32 v163, v96, v96
	v_fmac_f32_e32 v164, v98, v98
	v_add_f32_e32 v163, v163, v164
	v_add_f32_e32 v162, v162, v163
	v_mov_b32_e32 v163, v162
	s_nop 1
	v_permlane16_swap_b32_e32 v162, v163
	v_add_f32_e32 v162, v162, v163
	v_mov_b32_e32 v163, v162
	s_nop 1
	v_permlane32_swap_b32_e32 v162, v163
	v_add_f32_e32 v162, v162, v163
	s_lshl_b32 s17, s15, 8
	v_add_u32_e32 v165, s17, v209
	s_and_saveexec_b64 s[30:31], s[6:7]
	ds_write_b32 v165, v162
	s_mov_b64 exec, s[30:31]
	s_lshl_b32 s15, s1, 1
	s_add_i32 s15, s15, 1
	s_mul_i32 s16, s15, 0x2100
	s_lshl_b32 s17, s0, 7
	s_add_i32 s16, s16, s17
	v_add_u32_e32 v176, s16, v202
	ds_read_b64_tr_b16 v[64:65], v176 offset:0
	ds_read_b64_tr_b16 v[66:67], v176 offset:32
	ds_read_b64_tr_b16 v[68:69], v176 offset:64
	ds_read_b64_tr_b16 v[70:71], v176 offset:96
	ds_read_b64_tr_b16 v[116:117], v176 offset:8448
	ds_read_b64_tr_b16 v[118:119], v176 offset:8480
	ds_read_b64_tr_b16 v[120:121], v176 offset:8512
	ds_read_b64_tr_b16 v[122:123], v176 offset:8544
	v_add_u32_e32 v177, s16, v203
	ds_read_b64 v[154:155], v177 offset:4224
	ds_read_b64 v[156:157], v177 offset:4256
	ds_read_b64 v[158:159], v177 offset:4288
	ds_read_b64 v[160:161], v177 offset:4320
	s_lshl_b32 s17, s15, 4
	s_add_i32 s18, s14, s17
	v_add_u32_e32 v178, s18, v200
	v_sub_u32_e32 v179, v178, v208
	v_max_i32_e32 v179, 0, v179
	v_add_u32_e32 v180, v178, v208
	v_min_i32_e32 v180, s19, v180
	v_sub_u32_e32 v213, v180, v179
	s_add_i32 s18, s18, -8
	v_subrev_u32_e32 v212, s18, v179
	v_lshlrev_b32_e32 v181, 2, v201
	v_sub_u32_e32 v212, v212, v181
	v_sub_u32_e32 v184, 0, v212
	v_sub_u32_e32 v185, 1, v212
	v_sub_u32_e32 v186, 2, v212
	v_sub_u32_e32 v187, 3, v212
	v_cmp_lt_u32_e64 s[20:21], v184, v213
	v_cmp_lt_u32_e64 s[24:25], v185, v213
	v_cmp_lt_u32_e64 s[26:27], v186, v213
	v_cmp_lt_u32_e64 s[28:29], v187, v213
	v_cndmask_b32_e64 v184, 0, v204, s[20:21]
	v_cndmask_b32_e64 v185, 0, v205, s[24:25]
	v_cndmask_b32_e64 v186, 0, v204, s[26:27]
	v_cndmask_b32_e64 v187, 0, v205, s[28:29]
	v_or_b32_e32 v72, v184, v185
	v_or_b32_e32 v73, v186, v187
	v_sub_u32_e32 v184, 16, v212
	v_sub_u32_e32 v185, 17, v212
	v_sub_u32_e32 v186, 18, v212
	v_sub_u32_e32 v187, 19, v212
	v_cmp_lt_u32_e64 s[20:21], v184, v213
	v_cmp_lt_u32_e64 s[24:25], v185, v213
	v_cmp_lt_u32_e64 s[26:27], v186, v213
	v_cmp_lt_u32_e64 s[28:29], v187, v213
	v_cndmask_b32_e64 v184, 0, v204, s[20:21]
	v_cndmask_b32_e64 v185, 0, v205, s[24:25]
	v_cndmask_b32_e64 v186, 0, v204, s[26:27]
	v_cndmask_b32_e64 v187, 0, v205, s[28:29]
	v_or_b32_e32 v74, v184, v185
	v_or_b32_e32 v75, v186, v187
	v_cvt_f32_i32_e32 v188, v213
	v_div_scale_f32 v189, s[20:21], v188, v188, 1.0
	v_rcp_f32_e32 v190, v189
	v_div_scale_f32 v191, vcc, 1.0, v188, 1.0
	v_fma_f32 v192, -v189, v190, 1.0
	v_fmac_f32_e32 v190, v192, v190
	v_mul_f32_e32 v192, v191, v190
	v_fma_f32 v193, -v189, v192, v191
	v_fmac_f32_e32 v192, v193, v190
	v_fma_f32 v189, -v189, v192, v191
	s_nop 1
	v_div_fmas_f32 v189, v189, v190, v192
	v_div_fixup_f32 v172, v189, v188, 1.0
	s_waitcnt lgkmcnt(0)
	v_mfma_f32_16x16x16_bf16 v[48:51], v[64:65], v[72:73], 0
	v_mfma_f32_16x16x16_bf16 v[52:55], v[66:67], v[72:73], 0
	v_mfma_f32_16x16x16_bf16 v[56:59], v[68:69], v[72:73], 0
	v_mfma_f32_16x16x16_bf16 v[60:63], v[70:71], v[72:73], 0
	v_mfma_f32_16x16x16_bf16 v[48:51], v[116:117], v[74:75], v[48:51]
	v_mfma_f32_16x16x16_bf16 v[52:55], v[118:119], v[74:75], v[52:55]
	v_mfma_f32_16x16x16_bf16 v[56:59], v[120:121], v[74:75], v[56:59]
	v_mfma_f32_16x16x16_bf16 v[60:63], v[122:123], v[74:75], v[60:63]
	v_and_b32_e32 v167, 0xffff0000, v154
	v_lshlrev_b32_e32 v166, 16, v154
	v_and_b32_e32 v169, 0xffff0000, v155
	v_lshlrev_b32_e32 v168, 16, v155
	s_nop 0
	v_pk_fma_f32 v[48:49], v[48:49], v[172:173], v[166:167] op_sel_hi:[1,0,1] neg_lo:[0,0,1] neg_hi:[0,0,1]
	v_pk_fma_f32 v[50:51], v[50:51], v[172:173], v[168:169] op_sel_hi:[1,0,1] neg_lo:[0,0,1] neg_hi:[0,0,1]
	s_nop 0
	v_cvt_pk_bf16_f32 v76, v48, v49
	v_cvt_pk_bf16_f32 v77, v50, v51
	v_and_b32_e32 v167, 0xffff0000, v156
	v_lshlrev_b32_e32 v166, 16, v156
	v_and_b32_e32 v169, 0xffff0000, v157
	v_lshlrev_b32_e32 v168, 16, v157
	v_pk_fma_f32 v[52:53], v[52:53], v[172:173], v[166:167] op_sel_hi:[1,0,1] neg_lo:[0,0,1] neg_hi:[0,0,1]
	v_pk_fma_f32 v[54:55], v[54:55], v[172:173], v[168:169] op_sel_hi:[1,0,1] neg_lo:[0,0,1] neg_hi:[0,0,1]
	s_nop 0
	v_cvt_pk_bf16_f32 v78, v52, v53
	v_cvt_pk_bf16_f32 v79, v54, v55
	v_and_b32_e32 v167, 0xffff0000, v158
	v_lshlrev_b32_e32 v166, 16, v158
	v_and_b32_e32 v169, 0xffff0000, v159
	v_lshlrev_b32_e32 v168, 16, v159
	v_pk_fma_f32 v[56:57], v[56:57], v[172:173], v[166:167] op_sel_hi:[1,0,1] neg_lo:[0,0,1] neg_hi:[0,0,1]
	v_pk_fma_f32 v[58:59], v[58:59], v[172:173], v[168:169] op_sel_hi:[1,0,1] neg_lo:[0,0,1] neg_hi:[0,0,1]
	s_nop 0
	v_cvt_pk_bf16_f32 v80, v56, v57
	v_cvt_pk_bf16_f32 v81, v58, v59
	v_and_b32_e32 v167, 0xffff0000, v160
	v_lshlrev_b32_e32 v166, 16, v160
	v_and_b32_e32 v169, 0xffff0000, v161
	v_lshlrev_b32_e32 v168, 16, v161
	v_pk_fma_f32 v[60:61], v[60:61], v[172:173], v[166:167] op_sel_hi:[1,0,1] neg_lo:[0,0,1] neg_hi:[0,0,1]
	v_pk_fma_f32 v[62:63], v[62:63], v[172:173], v[168:169] op_sel_hi:[1,0,1] neg_lo:[0,0,1] neg_hi:[0,0,1]
	s_nop 0
	v_cvt_pk_bf16_f32 v82, v60, v61
	v_cvt_pk_bf16_f32 v83, v62, v63
	v_mfma_f32_16x16x16_bf16 v[100:103], v[0:1], v[76:77], 0
	v_mfma_f32_16x16x16_bf16 v[104:107], v[8:9], v[76:77], 0
	v_mfma_f32_16x16x16_bf16 v[108:111], v[16:17], v[76:77], 0
	v_mfma_f32_16x16x16_bf16 v[112:115], v[24:25], v[76:77], 0
	v_mfma_f32_16x16x16_bf16 v[100:103], v[2:3], v[78:79], v[100:103]
	v_mfma_f32_16x16x16_bf16 v[104:107], v[10:11], v[78:79], v[104:107]
	v_mfma_f32_16x16x16_bf16 v[108:111], v[18:19], v[78:79], v[108:111]
	v_mfma_f32_16x16x16_bf16 v[112:115], v[26:27], v[78:79], v[112:115]
	v_mfma_f32_16x16x16_bf16 v[100:103], v[4:5], v[80:81], v[100:103]
	v_mfma_f32_16x16x16_bf16 v[104:107], v[12:13], v[80:81], v[104:107]
	v_mfma_f32_16x16x16_bf16 v[108:111], v[20:21], v[80:81], v[108:111]
	v_mfma_f32_16x16x16_bf16 v[112:115], v[28:29], v[80:81], v[112:115]
	v_mfma_f32_16x16x16_bf16 v[100:103], v[6:7], v[82:83], v[100:103]
	v_mfma_f32_16x16x16_bf16 v[104:107], v[14:15], v[82:83], v[104:107]
	v_mfma_f32_16x16x16_bf16 v[108:111], v[22:23], v[82:83], v[108:111]
	v_mfma_f32_16x16x16_bf16 v[112:115], v[30:31], v[82:83], v[112:115]
	s_nop 4
	v_pk_mul_f32 v[100:101], v[100:101], v[32:33]
	v_pk_mul_f32 v[102:103], v[102:103], v[34:35]
	v_pk_mul_f32 v[104:105], v[104:105], v[36:37]
	v_pk_mul_f32 v[106:107], v[106:107], v[38:39]
	v_pk_mul_f32 v[108:109], v[108:109], v[40:41]
	v_pk_mul_f32 v[110:111], v[110:111], v[42:43]
	v_pk_mul_f32 v[112:113], v[112:113], v[44:45]
	v_pk_mul_f32 v[114:115], v[114:115], v[46:47]
	v_mul_f32_e32 v163, v101, v101
	v_mul_f32_e32 v164, v103, v103
	v_fmac_f32_e32 v163, v100, v100
	v_fmac_f32_e32 v164, v102, v102
	v_add_f32_e32 v162, v163, v164
	v_mul_f32_e32 v163, v105, v105
	v_mul_f32_e32 v164, v107, v107
	v_fmac_f32_e32 v163, v104, v104
	v_fmac_f32_e32 v164, v106, v106
	v_add_f32_e32 v163, v163, v164
	v_add_f32_e32 v162, v162, v163
	v_mul_f32_e32 v163, v109, v109
	v_mul_f32_e32 v164, v111, v111
	v_fmac_f32_e32 v163, v108, v108
	v_fmac_f32_e32 v164, v110, v110
	v_add_f32_e32 v163, v163, v164
	v_add_f32_e32 v162, v162, v163
	v_mul_f32_e32 v163, v113, v113
	v_mul_f32_e32 v164, v115, v115
	v_fmac_f32_e32 v163, v112, v112
	v_fmac_f32_e32 v164, v114, v114
	v_add_f32_e32 v163, v163, v164
	v_add_f32_e32 v162, v162, v163
	v_mov_b32_e32 v163, v162
	s_nop 1
	v_permlane16_swap_b32_e32 v162, v163
	v_add_f32_e32 v162, v162, v163
	v_mov_b32_e32 v163, v162
	s_nop 1
	v_permlane32_swap_b32_e32 v162, v163
	v_add_f32_e32 v162, v162, v163
	s_lshl_b32 s17, s15, 8
	v_add_u32_e32 v165, s17, v209
	s_and_saveexec_b64 s[30:31], s[6:7]
	ds_write_b32 v165, v162
	s_mov_b64 exec, s[30:31]
	s_waitcnt lgkmcnt(0)
	s_barrier
	s_lshl_b32 s5, s4, 6
	s_lshl_b32 s15, s1, 1
	s_lshl_b32 s17, s15, 8
	v_add_u32_e32 v176, s17, v210
	ds_read_b128 v[180:183], v176
	s_waitcnt lgkmcnt(0)
	v_add_f32_e32 v180, v180, v181
	v_add_f32_e32 v182, v182, v183
	v_add_f32_e32 v180, v180, v182
	v_mov_b32_e32 v192, 0x358637bd
	v_fmamk_f32 v180, v180, 0x3b800000, v192
	v_sqrt_f32_e32 v184, v180
	s_nop 0
	v_add_u32_e32 v185, -1, v184
	v_add_u32_e32 v186, 1, v184
	v_fma_f32 v187, -v185, v184, v180
	v_fma_f32 v188, -v186, v184, v180
	v_cmp_ge_f32_e64 s[20:21], 0, v187
	s_nop 1
	v_cndmask_b32_e64 v184, v184, v185, s[20:21]
	v_cmp_lt_f32_e64 s[20:21], 0, v188
	s_nop 1
	v_cndmask_b32_e64 v184, v184, v186, s[20:21]
	v_div_scale_f32 v185, s[20:21], v184, v184, 1.0
	v_rcp_f32_e32 v186, v185
	v_div_scale_f32 v187, vcc, 1.0, v184, 1.0
	v_fma_f32 v188, -v185, v186, 1.0
	v_fmac_f32_e32 v186, v188, v186
	v_mul_f32_e32 v188, v187, v186
	v_fma_f32 v189, -v185, v188, v187
	v_fmac_f32_e32 v188, v189, v186
	v_fma_f32 v185, -v185, v188, v187
	s_nop 1
	v_div_fmas_f32 v185, v185, v186, v188
	v_div_fixup_f32 v190, v185, v184, 1.0
	s_lshl_b32 s17, s15, 4
	s_add_i32 s17, s17, s5
	v_add_u32_e32 v177, s17, v200
	v_lshl_add_u32 v177, v177, 11, v211
	v_pk_mul_f32 v[84:85], v[84:85], v[190:191] op_sel_hi:[1,0]
	v_pk_mul_f32 v[86:87], v[86:87], v[190:191] op_sel_hi:[1,0]
	v_pk_mul_f32 v[88:89], v[88:89], v[190:191] op_sel_hi:[1,0]
	v_pk_mul_f32 v[90:91], v[90:91], v[190:191] op_sel_hi:[1,0]
	v_pk_mul_f32 v[92:93], v[92:93], v[190:191] op_sel_hi:[1,0]
	v_pk_mul_f32 v[94:95], v[94:95], v[190:191] op_sel_hi:[1,0]
	v_pk_mul_f32 v[96:97], v[96:97], v[190:191] op_sel_hi:[1,0]
	v_pk_mul_f32 v[98:99], v[98:99], v[190:191] op_sel_hi:[1,0]
	v_cvt_pk_bf16_f32 v84, v84, v85
	v_cvt_pk_bf16_f32 v85, v86, v87
	global_store_dwordx2 v177, v[84:85], s[12:13] offset:0
	v_cvt_pk_bf16_f32 v88, v88, v89
	v_cvt_pk_bf16_f32 v89, v90, v91
	global_store_dwordx2 v177, v[88:89], s[12:13] offset:32
	v_cvt_pk_bf16_f32 v92, v92, v93
	v_cvt_pk_bf16_f32 v93, v94, v95
	global_store_dwordx2 v177, v[92:93], s[12:13] offset:64
	v_cvt_pk_bf16_f32 v96, v96, v97
	v_cvt_pk_bf16_f32 v97, v98, v99
	global_store_dwordx2 v177, v[96:97], s[12:13] offset:96
	s_lshl_b32 s15, s1, 1
	s_add_i32 s15, s15, 1
	s_lshl_b32 s17, s15, 8
	v_add_u32_e32 v176, s17, v210
	ds_read_b128 v[180:183], v176
	s_waitcnt lgkmcnt(0)
	v_add_f32_e32 v180, v180, v181
	v_add_f32_e32 v182, v182, v183
	v_add_f32_e32 v180, v180, v182
	v_mov_b32_e32 v192, 0x358637bd
	v_fmamk_f32 v180, v180, 0x3b800000, v192
	v_sqrt_f32_e32 v184, v180
	s_nop 0
	v_add_u32_e32 v185, -1, v184
	v_add_u32_e32 v186, 1, v184
	v_fma_f32 v187, -v185, v184, v180
	v_fma_f32 v188, -v186, v184, v180
	v_cmp_ge_f32_e64 s[20:21], 0, v187
	s_nop 1
	v_cndmask_b32_e64 v184, v184, v185, s[20:21]
	v_cmp_lt_f32_e64 s[20:21], 0, v188
	s_nop 1
	v_cndmask_b32_e64 v184, v184, v186, s[20:21]
	v_div_scale_f32 v185, s[20:21], v184, v184, 1.0
	v_rcp_f32_e32 v186, v185
	v_div_scale_f32 v187, vcc, 1.0, v184, 1.0
	v_fma_f32 v188, -v185, v186, 1.0
	v_fmac_f32_e32 v186, v188, v186
	v_mul_f32_e32 v188, v187, v186
	v_fma_f32 v189, -v185, v188, v187
	v_fmac_f32_e32 v188, v189, v186
	v_fma_f32 v185, -v185, v188, v187
	s_nop 1
	v_div_fmas_f32 v185, v185, v186, v188
	v_div_fixup_f32 v190, v185, v184, 1.0
	s_lshl_b32 s17, s15, 4
	s_add_i32 s17, s17, s5
	v_add_u32_e32 v177, s17, v200
	v_lshl_add_u32 v177, v177, 11, v211
	v_pk_mul_f32 v[100:101], v[100:101], v[190:191] op_sel_hi:[1,0]
	v_pk_mul_f32 v[102:103], v[102:103], v[190:191] op_sel_hi:[1,0]
	v_pk_mul_f32 v[104:105], v[104:105], v[190:191] op_sel_hi:[1,0]
	v_pk_mul_f32 v[106:107], v[106:107], v[190:191] op_sel_hi:[1,0]
	v_pk_mul_f32 v[108:109], v[108:109], v[190:191] op_sel_hi:[1,0]
	v_pk_mul_f32 v[110:111], v[110:111], v[190:191] op_sel_hi:[1,0]
	v_pk_mul_f32 v[112:113], v[112:113], v[190:191] op_sel_hi:[1,0]
	v_pk_mul_f32 v[114:115], v[114:115], v[190:191] op_sel_hi:[1,0]
	v_cvt_pk_bf16_f32 v100, v100, v101
	v_cvt_pk_bf16_f32 v101, v102, v103
	global_store_dwordx2 v177, v[100:101], s[12:13] offset:0
	v_cvt_pk_bf16_f32 v104, v104, v105
	v_cvt_pk_bf16_f32 v105, v106, v107
	global_store_dwordx2 v177, v[104:105], s[12:13] offset:32
	v_cvt_pk_bf16_f32 v108, v108, v109
	v_cvt_pk_bf16_f32 v109, v110, v111
	global_store_dwordx2 v177, v[108:109], s[12:13] offset:64
	v_cvt_pk_bf16_f32 v112, v112, v113
	v_cvt_pk_bf16_f32 v113, v114, v115
	global_store_dwordx2 v177, v[112:113], s[12:13] offset:96
	s_mov_b32 s14, s98
	s_mov_b32 s19, s100
	s_add_i32 s4, s4, s66
	s_cmpk_lt_i32 s4, 0x300
	s_cbranch_scc1 .Lpx_item
